# P9 row-panel partial sums reduced cooperatively in one load batch (on top of v78)
# baseline (speedup 1.0000x reference)
; __device__ __forceinline__ float rstd_from(const float* ssq, int row) {
;     const f32x4* p = (const f32x4*)(ssq + (size_t)row * 16);
;     const f32x4 s = (p[0] + p[1]) + (p[2] + p[3]);
;     return __builtin_amdgcn_rsqf(((s[0] + s[1]) + (s[2] + s[3])) * (1.0f / DM) + RMS_EPS);
; }
; __device__ __forceinline__ void p10_final(const Args& A, int lane, int wave, float* outp) {
;     const float* ssq = (const float*)(A.ws + WS_SSQF); const bf16_t* X3 = (const bf16_t*)(A.ws + WS_X3);
;     const int gw = blockIdx.x * 8 + wave, NGW = gridDim.x * 8;
;     for (int m = gw; m < M; m += NGW) { const float rs = pg8::rstd_from(ssq, m);
; #pragma unroll
;         for (int j = 0; j < 2; ++j) { const int c = 8 * lane + 512 * j; f32x4 a, b; pg8::unpack8(*(const u32x4*)(X3 + (size_t)m * DM + c), a, b);
;             *(f32x4*)(outp + (size_t)m * DM + c) = (a * rs) * *(const f32x4*)(A.g_final + c); *(f32x4*)(outp + (size_t)m * DM + c + 4) = (b * rs) * *(const f32x4*)(A.g_final + c + 4); } }
; }
.Lf9_sync_done:
	s_or_b64 exec, exec, s[30:31]
	s_barrier
	s_waitcnt lgkmcnt(0)
	s_lshl_b32 s4, s0, 2
	s_add_u32 s4, s100, s4
	s_addc_u32 s5, s101, 0
	global_load_dwordx4 v[168:171], v188, s[4:5]
	global_load_dwordx4 v[164:167], v188, s[4:5] offset:16
	global_load_dwordx4 v[160:163], v188, s[4:5] offset:128
	global_load_dwordx4 v[156:159], v188, s[4:5] offset:144
	s_lshl_b32 s4, s1, 6
	s_add_u32 s38, s16, s4
	s_addc_u32 s39, s17, 0
	s_add_u32 s36, s38, 0x2000
	s_addc_u32 s37, s39, 0
	v_mov_b32_e32 v189, 0x358637bd
	v_lshl_add_u32 v228, v190, 10, v146
	global_load_dwordx4 v[196:199], v228, s[38:39] sc0 sc1
	global_load_dwordx4 v[200:203], v228, s[38:39] offset:16 sc0 sc1
	global_load_dwordx4 v[204:207], v228, s[38:39] offset:32 sc0 sc1
	global_load_dwordx4 v[208:211], v228, s[38:39] offset:48 sc0 sc1
	global_load_dwordx4 v[212:215], v228, s[36:37] sc0 sc1
	global_load_dwordx4 v[216:219], v228, s[36:37] offset:16 sc0 sc1
	global_load_dwordx4 v[240:243], v228, s[36:37] offset:32 sc0 sc1
	global_load_dwordx4 v[244:247], v228, s[36:37] offset:48 sc0 sc1
	v_lshlrev_b32_e32 v229, 2, v1
	v_add_u32_e32 v230, 0x40, v229
	v_add_u32_e32 v231, 0x80, v229
	v_add_u32_e32 v232, 0xc0, v229
	s_waitcnt vmcnt(4)
	v_pk_add_f32 v[198:199], v[198:199], v[202:203]
	v_pk_add_f32 v[196:197], v[196:197], v[200:201]
	v_pk_add_f32 v[200:201], v[206:207], v[210:211]
	v_pk_add_f32 v[202:203], v[204:205], v[208:209]
	v_pk_add_f32 v[198:199], v[198:199], v[200:201]
	v_pk_add_f32 v[196:197], v[196:197], v[202:203]
	v_add_f32_e32 v196, v196, v197
	v_add_f32_e32 v198, v198, v199
	v_add_f32_e32 v196, v196, v198
	v_fmamk_f32 v196, v196, 0x3a800000, v189
	v_rsq_f32_e32 v196, v196
	s_waitcnt vmcnt(0)
	v_pk_add_f32 v[214:215], v[214:215], v[218:219]
	v_pk_add_f32 v[212:213], v[212:213], v[216:217]
	v_pk_add_f32 v[216:217], v[242:243], v[246:247]
	v_pk_add_f32 v[218:219], v[240:241], v[244:245]
	v_pk_add_f32 v[214:215], v[214:215], v[216:217]
	v_pk_add_f32 v[212:213], v[212:213], v[218:219]
	v_add_f32_e32 v212, v212, v213
	v_add_f32_e32 v214, v214, v215
	v_add_f32_e32 v212, v212, v214
	v_fmamk_f32 v212, v212, 0x3a800000, v189
	v_rsq_f32_e32 v212, v212
	s_nop 0
	ds_bpermute_b32 v172, v229, v196
	ds_bpermute_b32 v173, v230, v196
	ds_bpermute_b32 v174, v231, v196
	ds_bpermute_b32 v175, v232, v196
	ds_bpermute_b32 v176, v229, v212
	ds_bpermute_b32 v177, v230, v212
	ds_bpermute_b32 v178, v231, v212
	ds_bpermute_b32 v179, v232, v212
	s_waitcnt lgkmcnt(0)
	s_lshl_b32 s4, s54, 7
	s_lshl_b32 s5, s53, 11
	s_add_i32 s4, s4, s5
	s_add_i32 s4, s4, 0x20000
	v_lshlrev_b32_e32 v228, 7, v1
	v_lshl_add_u32 v228, v190, 5, v228
	v_add_u32_e32 v228, s4, v228
	v_lshl_add_u32 v229, v195, 4, s4
	v_lshrrev_b32_e32 v230, 3, v195
	v_lshlrev_b32_e32 v230, 12, v230
	v_and_b32_e32 v231, 7, v195
	v_lshl_add_u32 v230, v231, 4, v230
	v_add_u32_e32 v231, 0x8000, v230
	s_lshl_b32 s4, s1, 12
	s_lshl_b32 s5, s0, 2
	s_add_u32 s4, s4, s5
	s_add_u32 s34, s76, s4
	s_addc_u32 s35, s77, 0
	v_mul_f32_e32 v196, v172, v114
	v_mul_f32_e32 v197, v172, v115
	v_mul_f32_e32 v198, v172, v116
	v_mul_f32_e32 v199, v172, v117
	v_mul_f32_e32 v200, v172, v118
	v_mul_f32_e32 v201, v172, v119
	v_mul_f32_e32 v202, v172, v120
	v_mul_f32_e32 v203, v172, v121
	v_mul_f32_e32 v204, v172, v122
	v_mul_f32_e32 v205, v172, v123
	v_mul_f32_e32 v206, v172, v124
	v_mul_f32_e32 v207, v172, v125
	v_mul_f32_e32 v208, v172, v126
	v_mul_f32_e32 v209, v172, v127
	v_mul_f32_e32 v210, v172, v128
	v_mul_f32_e32 v211, v172, v129
	v_pk_mul_f32 v[196:197], v[156:157], v[196:197]
	v_pk_mul_f32 v[198:199], v[158:159], v[198:199]
	v_pk_mul_f32 v[200:201], v[160:161], v[200:201]
	v_pk_mul_f32 v[202:203], v[162:163], v[202:203]
	v_pk_mul_f32 v[204:205], v[164:165], v[204:205]
	v_pk_mul_f32 v[206:207], v[166:167], v[206:207]
	v_pk_mul_f32 v[208:209], v[168:169], v[208:209]
	v_pk_mul_f32 v[210:211], v[170:171], v[210:211]
	ds_write_b128 v228, v[208:211]
	ds_write_b128 v228, v[204:207] offset:16
	ds_read_b128 v[232:235], v229
	ds_read_b128 v[236:239], v229 offset:1024
	s_waitcnt lgkmcnt(1)
	global_store_dwordx4 v230, v[232:235], s[34:35]
	s_waitcnt lgkmcnt(0)
	global_store_dwordx4 v231, v[236:239], s[34:35]
	ds_write_b128 v228, v[200:203]
	ds_write_b128 v228, v[196:199] offset:16
	ds_read_b128 v[240:243], v229
	ds_read_b128 v[244:247], v229 offset:1024
	s_waitcnt lgkmcnt(1)
	global_store_dwordx4 v230, v[240:243], s[34:35] offset:128
	s_waitcnt lgkmcnt(0)
	global_store_dwordx4 v231, v[244:247], s[34:35] offset:128
	s_add_u32 s34, s34, 0x10000
	s_addc_u32 s35, s35, 0
	v_mul_f32_e32 v212, v173, v98
	v_mul_f32_e32 v213, v173, v99
	v_mul_f32_e32 v214, v173, v100
	v_mul_f32_e32 v215, v173, v101
	v_mul_f32_e32 v216, v173, v102
	v_mul_f32_e32 v217, v173, v103
	v_mul_f32_e32 v218, v173, v104
	v_mul_f32_e32 v219, v173, v105
	v_mul_f32_e32 v220, v173, v106
	v_mul_f32_e32 v221, v173, v107
	v_mul_f32_e32 v222, v173, v108
	v_mul_f32_e32 v223, v173, v109
	v_mul_f32_e32 v224, v173, v110
	v_mul_f32_e32 v225, v173, v111
	v_mul_f32_e32 v226, v173, v112
	v_mul_f32_e32 v227, v173, v113
	v_pk_mul_f32 v[212:213], v[156:157], v[212:213]
	v_pk_mul_f32 v[214:215], v[158:159], v[214:215]
	v_pk_mul_f32 v[216:217], v[160:161], v[216:217]
	v_pk_mul_f32 v[218:219], v[162:163], v[218:219]
	v_pk_mul_f32 v[220:221], v[164:165], v[220:221]
	v_pk_mul_f32 v[222:223], v[166:167], v[222:223]
	v_pk_mul_f32 v[224:225], v[168:169], v[224:225]
	v_pk_mul_f32 v[226:227], v[170:171], v[226:227]
	ds_write_b128 v228, v[224:227]
	ds_write_b128 v228, v[220:223] offset:16
	ds_read_b128 v[240:243], v229
	ds_read_b128 v[244:247], v229 offset:1024
	s_waitcnt lgkmcnt(1)
	global_store_dwordx4 v230, v[240:243], s[34:35]
	s_waitcnt lgkmcnt(0)
; __device__ __forceinline__ void p10_final(const Args& A, int lane, int wave, float* outp) {
;     const float* ssq = (const float*)(A.ws + WS_SSQF); const bf16_t* X3 = (const bf16_t*)(A.ws + WS_X3);
;     const int gw = blockIdx.x * 8 + wave, NGW = gridDim.x * 8;
;     for (int m = gw; m < M; m += NGW) { const float rs = pg8::rstd_from(ssq, m);
; #pragma unroll
;         for (int j = 0; j < 2; ++j) { const int c = 8 * lane + 512 * j; f32x4 a, b; pg8::unpack8(*(const u32x4*)(X3 + (size_t)m * DM + c), a, b);
;             *(f32x4*)(outp + (size_t)m * DM + c) = (a * rs) * *(const f32x4*)(A.g_final + c); *(f32x4*)(outp + (size_t)m * DM + c + 4) = (b * rs) * *(const f32x4*)(A.g_final + c + 4); } }
; }
	global_store_dwordx4 v231, v[244:247], s[34:35]
	ds_write_b128 v228, v[216:219]
	ds_write_b128 v228, v[212:215] offset:16
	ds_read_b128 v[240:243], v229
	ds_read_b128 v[244:247], v229 offset:1024
	s_waitcnt lgkmcnt(1)
	global_store_dwordx4 v230, v[240:243], s[34:35] offset:128
	s_waitcnt lgkmcnt(0)
	global_store_dwordx4 v231, v[244:247], s[34:35] offset:128
	s_add_u32 s34, s34, 0x10000
	s_addc_u32 s35, s35, 0
	v_mul_f32_e32 v196, v174, v82
	v_mul_f32_e32 v197, v174, v83
	v_mul_f32_e32 v198, v174, v84
	v_mul_f32_e32 v199, v174, v85
	v_mul_f32_e32 v200, v174, v86
	v_mul_f32_e32 v201, v174, v87
	v_mul_f32_e32 v202, v174, v88
	v_mul_f32_e32 v203, v174, v89
	v_mul_f32_e32 v204, v174, v90
	v_mul_f32_e32 v205, v174, v91
	v_mul_f32_e32 v206, v174, v92
	v_mul_f32_e32 v207, v174, v93
	v_mul_f32_e32 v208, v174, v94
	v_mul_f32_e32 v209, v174, v95
	v_mul_f32_e32 v210, v174, v96
	v_mul_f32_e32 v211, v174, v97
	v_pk_mul_f32 v[196:197], v[156:157], v[196:197]
	v_pk_mul_f32 v[198:199], v[158:159], v[198:199]
	v_pk_mul_f32 v[200:201], v[160:161], v[200:201]
	v_pk_mul_f32 v[202:203], v[162:163], v[202:203]
	v_pk_mul_f32 v[204:205], v[164:165], v[204:205]
	v_pk_mul_f32 v[206:207], v[166:167], v[206:207]
	v_pk_mul_f32 v[208:209], v[168:169], v[208:209]
	v_pk_mul_f32 v[210:211], v[170:171], v[210:211]
	ds_write_b128 v228, v[208:211]
	ds_write_b128 v228, v[204:207] offset:16
	ds_read_b128 v[232:235], v229
	ds_read_b128 v[236:239], v229 offset:1024
	s_waitcnt lgkmcnt(1)
	global_store_dwordx4 v230, v[232:235], s[34:35]
	s_waitcnt lgkmcnt(0)
	global_store_dwordx4 v231, v[236:239], s[34:35]
	ds_write_b128 v228, v[200:203]
	ds_write_b128 v228, v[196:199] offset:16
	ds_read_b128 v[240:243], v229
	ds_read_b128 v[244:247], v229 offset:1024
	s_waitcnt lgkmcnt(1)
	global_store_dwordx4 v230, v[240:243], s[34:35] offset:128
	s_waitcnt lgkmcnt(0)
	global_store_dwordx4 v231, v[244:247], s[34:35] offset:128
	s_add_u32 s34, s34, 0x10000
	s_addc_u32 s35, s35, 0
	v_mul_f32_e32 v212, v175, v66
	v_mul_f32_e32 v213, v175, v67
	v_mul_f32_e32 v214, v175, v68
	v_mul_f32_e32 v215, v175, v69
	v_mul_f32_e32 v216, v175, v70
	v_mul_f32_e32 v217, v175, v71
	v_mul_f32_e32 v218, v175, v72
	v_mul_f32_e32 v219, v175, v73
	v_mul_f32_e32 v220, v175, v74
	v_mul_f32_e32 v221, v175, v75
	v_mul_f32_e32 v222, v175, v76
	v_mul_f32_e32 v223, v175, v77
	v_mul_f32_e32 v224, v175, v78
	v_mul_f32_e32 v225, v175, v79
	v_mul_f32_e32 v226, v175, v80
	v_mul_f32_e32 v227, v175, v81
	v_pk_mul_f32 v[212:213], v[156:157], v[212:213]
	v_pk_mul_f32 v[214:215], v[158:159], v[214:215]
	v_pk_mul_f32 v[216:217], v[160:161], v[216:217]
	v_pk_mul_f32 v[218:219], v[162:163], v[218:219]
	v_pk_mul_f32 v[220:221], v[164:165], v[220:221]
	v_pk_mul_f32 v[222:223], v[166:167], v[222:223]
	v_pk_mul_f32 v[224:225], v[168:169], v[224:225]
	v_pk_mul_f32 v[226:227], v[170:171], v[226:227]
	ds_write_b128 v228, v[224:227]
	ds_write_b128 v228, v[220:223] offset:16
	ds_read_b128 v[240:243], v229
	ds_read_b128 v[244:247], v229 offset:1024
	s_waitcnt lgkmcnt(1)
	global_store_dwordx4 v230, v[240:243], s[34:35]
	s_waitcnt lgkmcnt(0)
	global_store_dwordx4 v231, v[244:247], s[34:35]
	ds_write_b128 v228, v[216:219]
	ds_write_b128 v228, v[212:215] offset:16
	ds_read_b128 v[240:243], v229
	ds_read_b128 v[244:247], v229 offset:1024
	s_waitcnt lgkmcnt(1)
	global_store_dwordx4 v230, v[240:243], s[34:35] offset:128
	s_waitcnt lgkmcnt(0)
	global_store_dwordx4 v231, v[244:247], s[34:35] offset:128
	s_add_u32 s34, s34, 0x50000
	s_addc_u32 s35, s35, 0
	v_mul_f32_e32 v196, v176, v50
	v_mul_f32_e32 v197, v176, v51
	v_mul_f32_e32 v198, v176, v52
	v_mul_f32_e32 v199, v176, v53
	v_mul_f32_e32 v200, v176, v54
	v_mul_f32_e32 v201, v176, v55
	v_mul_f32_e32 v202, v176, v56
	v_mul_f32_e32 v203, v176, v57
	v_mul_f32_e32 v204, v176, v58
	v_mul_f32_e32 v205, v176, v59
	v_mul_f32_e32 v206, v176, v60
	v_mul_f32_e32 v207, v176, v61
	v_mul_f32_e32 v208, v176, v62
	v_mul_f32_e32 v209, v176, v63
	v_mul_f32_e32 v210, v176, v64
	v_mul_f32_e32 v211, v176, v65
	v_pk_mul_f32 v[196:197], v[156:157], v[196:197]
	v_pk_mul_f32 v[198:199], v[158:159], v[198:199]
	v_pk_mul_f32 v[200:201], v[160:161], v[200:201]
	v_pk_mul_f32 v[202:203], v[162:163], v[202:203]
	v_pk_mul_f32 v[204:205], v[164:165], v[204:205]
	v_pk_mul_f32 v[206:207], v[166:167], v[206:207]
	v_pk_mul_f32 v[208:209], v[168:169], v[208:209]
	v_pk_mul_f32 v[210:211], v[170:171], v[210:211]
	ds_write_b128 v228, v[208:211]
	ds_write_b128 v228, v[204:207] offset:16
	ds_read_b128 v[232:235], v229
	ds_read_b128 v[236:239], v229 offset:1024
	s_waitcnt lgkmcnt(1)
	global_store_dwordx4 v230, v[232:235], s[34:35]
	s_waitcnt lgkmcnt(0)
	global_store_dwordx4 v231, v[236:239], s[34:35]
	ds_write_b128 v228, v[200:203]
	ds_write_b128 v228, v[196:199] offset:16
	ds_read_b128 v[240:243], v229
	ds_read_b128 v[244:247], v229 offset:1024
	s_waitcnt lgkmcnt(1)
	global_store_dwordx4 v230, v[240:243], s[34:35] offset:128
	s_waitcnt lgkmcnt(0)
; __device__ __forceinline__ void p10_final(const Args& A, int lane, int wave, float* outp) {
;     const float* ssq = (const float*)(A.ws + WS_SSQF); const bf16_t* X3 = (const bf16_t*)(A.ws + WS_X3);
;     const int gw = blockIdx.x * 8 + wave, NGW = gridDim.x * 8;
;     for (int m = gw; m < M; m += NGW) { const float rs = pg8::rstd_from(ssq, m);
; #pragma unroll
;         for (int j = 0; j < 2; ++j) { const int c = 8 * lane + 512 * j; f32x4 a, b; pg8::unpack8(*(const u32x4*)(X3 + (size_t)m * DM + c), a, b);
;             *(f32x4*)(outp + (size_t)m * DM + c) = (a * rs) * *(const f32x4*)(A.g_final + c); *(f32x4*)(outp + (size_t)m * DM + c + 4) = (b * rs) * *(const f32x4*)(A.g_final + c + 4); } }
; }
	global_store_dwordx4 v231, v[244:247], s[34:35] offset:128
	s_add_u32 s34, s34, 0x10000
	s_addc_u32 s35, s35, 0
	v_mul_f32_e32 v212, v177, v34
	v_mul_f32_e32 v213, v177, v35
	v_mul_f32_e32 v214, v177, v36
	v_mul_f32_e32 v215, v177, v37
	v_mul_f32_e32 v216, v177, v38
	v_mul_f32_e32 v217, v177, v39
	v_mul_f32_e32 v218, v177, v40
	v_mul_f32_e32 v219, v177, v41
	v_mul_f32_e32 v220, v177, v42
	v_mul_f32_e32 v221, v177, v43
	v_mul_f32_e32 v222, v177, v44
	v_mul_f32_e32 v223, v177, v45
	v_mul_f32_e32 v224, v177, v46
	v_mul_f32_e32 v225, v177, v47
	v_mul_f32_e32 v226, v177, v48
	v_mul_f32_e32 v227, v177, v49
	v_pk_mul_f32 v[212:213], v[156:157], v[212:213]
	v_pk_mul_f32 v[214:215], v[158:159], v[214:215]
	v_pk_mul_f32 v[216:217], v[160:161], v[216:217]
	v_pk_mul_f32 v[218:219], v[162:163], v[218:219]
	v_pk_mul_f32 v[220:221], v[164:165], v[220:221]
	v_pk_mul_f32 v[222:223], v[166:167], v[222:223]
	v_pk_mul_f32 v[224:225], v[168:169], v[224:225]
	v_pk_mul_f32 v[226:227], v[170:171], v[226:227]
	ds_write_b128 v228, v[224:227]
	ds_write_b128 v228, v[220:223] offset:16
	ds_read_b128 v[240:243], v229
	ds_read_b128 v[244:247], v229 offset:1024
	s_waitcnt lgkmcnt(1)
	global_store_dwordx4 v230, v[240:243], s[34:35]
	s_waitcnt lgkmcnt(0)
	global_store_dwordx4 v231, v[244:247], s[34:35]
	ds_write_b128 v228, v[216:219]
	ds_write_b128 v228, v[212:215] offset:16
	ds_read_b128 v[240:243], v229
	ds_read_b128 v[244:247], v229 offset:1024
	s_waitcnt lgkmcnt(1)
	global_store_dwordx4 v230, v[240:243], s[34:35] offset:128
	s_waitcnt lgkmcnt(0)
	global_store_dwordx4 v231, v[244:247], s[34:35] offset:128
	s_add_u32 s34, s34, 0x10000
	s_addc_u32 s35, s35, 0
	v_mul_f32_e32 v196, v178, v18
	v_mul_f32_e32 v197, v178, v19
	v_mul_f32_e32 v198, v178, v20
	v_mul_f32_e32 v199, v178, v21
	v_mul_f32_e32 v200, v178, v22
	v_mul_f32_e32 v201, v178, v23
	v_mul_f32_e32 v202, v178, v24
	v_mul_f32_e32 v203, v178, v25
	v_mul_f32_e32 v204, v178, v26
	v_mul_f32_e32 v205, v178, v27
	v_mul_f32_e32 v206, v178, v28
	v_mul_f32_e32 v207, v178, v29
	v_mul_f32_e32 v208, v178, v30
	v_mul_f32_e32 v209, v178, v31
	v_mul_f32_e32 v210, v178, v32
	v_mul_f32_e32 v211, v178, v33
	v_pk_mul_f32 v[196:197], v[156:157], v[196:197]
	v_pk_mul_f32 v[198:199], v[158:159], v[198:199]
	v_pk_mul_f32 v[200:201], v[160:161], v[200:201]
	v_pk_mul_f32 v[202:203], v[162:163], v[202:203]
	v_pk_mul_f32 v[204:205], v[164:165], v[204:205]
	v_pk_mul_f32 v[206:207], v[166:167], v[206:207]
	v_pk_mul_f32 v[208:209], v[168:169], v[208:209]
	v_pk_mul_f32 v[210:211], v[170:171], v[210:211]
	ds_write_b128 v228, v[208:211]
	ds_write_b128 v228, v[204:207] offset:16
	ds_read_b128 v[232:235], v229
	ds_read_b128 v[236:239], v229 offset:1024
	s_waitcnt lgkmcnt(1)
	global_store_dwordx4 v230, v[232:235], s[34:35]
	s_waitcnt lgkmcnt(0)
	global_store_dwordx4 v231, v[236:239], s[34:35]
	ds_write_b128 v228, v[200:203]
	ds_write_b128 v228, v[196:199] offset:16
	ds_read_b128 v[240:243], v229
	ds_read_b128 v[244:247], v229 offset:1024
	s_waitcnt lgkmcnt(1)
	global_store_dwordx4 v230, v[240:243], s[34:35] offset:128
	s_waitcnt lgkmcnt(0)
	global_store_dwordx4 v231, v[244:247], s[34:35] offset:128
	s_add_u32 s34, s34, 0x10000
	s_addc_u32 s35, s35, 0
	v_mul_f32_e32 v212, v179, v2
	v_mul_f32_e32 v213, v179, v3
	v_mul_f32_e32 v214, v179, v4
	v_mul_f32_e32 v215, v179, v5
	v_mul_f32_e32 v216, v179, v6
	v_mul_f32_e32 v217, v179, v7
	v_mul_f32_e32 v218, v179, v8
	v_mul_f32_e32 v219, v179, v9
	v_mul_f32_e32 v220, v179, v10
	v_mul_f32_e32 v221, v179, v11
	v_mul_f32_e32 v222, v179, v12
	v_mul_f32_e32 v223, v179, v13
	v_mul_f32_e32 v224, v179, v14
	v_mul_f32_e32 v225, v179, v15
	v_mul_f32_e32 v226, v179, v16
	v_mul_f32_e32 v227, v179, v17
	v_pk_mul_f32 v[212:213], v[156:157], v[212:213]
	v_pk_mul_f32 v[214:215], v[158:159], v[214:215]
	v_pk_mul_f32 v[216:217], v[160:161], v[216:217]
	v_pk_mul_f32 v[218:219], v[162:163], v[218:219]
	v_pk_mul_f32 v[220:221], v[164:165], v[220:221]
	v_pk_mul_f32 v[222:223], v[166:167], v[222:223]
	v_pk_mul_f32 v[224:225], v[168:169], v[224:225]
	v_pk_mul_f32 v[226:227], v[170:171], v[226:227]
	ds_write_b128 v228, v[224:227]
	ds_write_b128 v228, v[220:223] offset:16
	ds_read_b128 v[240:243], v229
	ds_read_b128 v[244:247], v229 offset:1024
	s_waitcnt lgkmcnt(1)
	global_store_dwordx4 v230, v[240:243], s[34:35]
	s_waitcnt lgkmcnt(0)
	global_store_dwordx4 v231, v[244:247], s[34:35]
	ds_write_b128 v228, v[216:219]
	ds_write_b128 v228, v[212:215] offset:16
	ds_read_b128 v[240:243], v229
	ds_read_b128 v[244:247], v229 offset:1024
	s_waitcnt lgkmcnt(1)
	global_store_dwordx4 v230, v[240:243], s[34:35] offset:128
	s_waitcnt lgkmcnt(0)
	global_store_dwordx4 v231, v[244:247], s[34:35] offset:128
	s_and_b64 vcc, exec, s[2:3]
	s_mov_b64 s[0:1], -1
	s_cbranch_vccnz .LBB0_1057
	s_andn2_b64 vcc, exec, s[14:15]
	s_cbranch_vccnz .LBB0_1056
	s_barrier
	s_branch .LBB0_1056
